# PB attention: K/V staging de-serialised (12 loads in flight, clamp+cndmask), sb0 Q loads and sink load hoisted above staging
# speedup vs baseline: 1.0136x; 1.0014x over previous
; #define LAS __attribute__((address_space(3)))
; __device__ __forceinline__ void attn_unit(LAS unsigned char* lds, const bf16* PROJ, bf16* DA, const float* sinkl, int unit, int tid, int wid, int lane) {
;     ...
;     for (int hp = 0; hp < 2; ++hp) {
;         v4u kreg[3], vreg[3];
; #pragma unroll
;         for (int i = 0; i < 3; ++i) {
;             const int idx = tid + 512 * (3 * hp + i), c = idx >> 3, ch = idx & 7, s = s0 + c;
;             if (s >= 0 && s < SEQ) { const bf16* p = PROJ + (rowb + s) * INW + 1024 + hk * 64 + ch * 8; kreg[i] = *(const v4u*)p; vreg[i] = *(const v4u*)(p + 128); }
;             else { kreg[i] = (v4u){0u, 0u, 0u, 0u}; vreg[i] = (v4u){0u, 0u, 0u, 0u}; }
;         }
; #pragma unroll
;         for (int i = 0; i < 3; ++i) {
;             const int idx = tid + 512 * (3 * hp + i), c = idx >> 3, ch = idx & 7;
;             *(LAS v4u*)(Ks + c * KS_PITCH + ch * 8) = kreg[i];
;             LAS bf16* vp = Vt + (ch * 8) * VT_PITCH + c;
;             vp[0 * VT_PITCH] = (bf16)(vreg[i].x & 0xffffu); vp[1 * VT_PITCH] = (bf16)(vreg[i].x >> 16);
;             vp[2 * VT_PITCH] = (bf16)(vreg[i].y & 0xffffu); vp[3 * VT_PITCH] = (bf16)(vreg[i].y >> 16);
;             vp[4 * VT_PITCH] = (bf16)(vreg[i].z & 0xffffu); vp[5 * VT_PITCH] = (bf16)(vreg[i].z >> 16);
;             vp[6 * VT_PITCH] = (bf16)(vreg[i].w & 0xffffu); vp[7 * VT_PITCH] = (bf16)(vreg[i].w >> 16);
;         }
;     ...
;     const float sink2 = sinkl[hq] * LOG2E;
;     const float NEG = -INFINITY;
;     const bool edge_n = (n == 0) || (n == 31);
; #pragma unroll 1
;     for (int sb = 0; sb < 2; ++sb) {
;         const int a0 = 64 * (wid & 1) + 32 * sb, a = a0 + r32;
;         const size_t qrow = rowb + (size_t)n * 128 + a;
;         bf16x8 qf[4];
; #pragma unroll
;         for (int ks = 0; ks < 4; ++ks) qf[ks] = *(const bf16x8*)(PROJ + qrow * INW + 512 + hq * 64 + ks * 16 + hi * 8);
.LBB0_284:
	s_and_b32 s25, s24, 31
	s_ashr_i32 s28, s24, 6
	s_ashr_i32 s29, s28, 31
	s_lshl_b32 s26, s25, 7
	s_lshl_b64 s[74:75], s[28:29], 12
	s_add_i32 s29, s26, 0xffffff80
	s_bfe_u32 s27, s24, 0x10005
	s_movk_i32 s6, 0x1000
	s_lshl_b32 s28, s27, 6
	s_lshl_b32 s84, s28, 1
	v_lshlrev_b32_e32 v38, 1, v84
	v_mov_b32_e32 v39, v66
	s_lshl_b32 s38, s27, 2
	s_add_i32 s38, s38, s62
	s_lshl_b32 s40, s38, 7
	s_mov_b32 s41, 0
	v_lshl_add_u64 v[54:55], v[88:89], 0, s[40:41]
	v_or_b32_e32 v52, s80, v112
	v_or_b32_e32 v52, s26, v52
	v_or_b32_e32 v52, s74, v52
	v_mad_u64_u32 v[54:55], s[30:31], v52, s82, v[54:55]
	v_mad_i32_i24 v55, s75, v201, v55
	global_load_dwordx4 v[68:71], v[54:55], off offset:1024
	global_load_dwordx4 v[72:75], v[54:55], off offset:1056
	global_load_dwordx4 v[76:79], v[54:55], off offset:1088
	global_load_dwordx4 v[80:83], v[54:55], off offset:1120
	s_lshl_b32 s39, s38, 2
	v_mov_b32_e32 v57, s39
	global_load_dword v56, v57, s[72:73]
	v_add_u32_e32 v52, s29, v85
	v_cmp_gt_u32_e64 s[42:43], s6, v52
	v_and_b32_e32 v52, 0xfff, v52
	v_or_b32_e32 v53, s74, v52
	v_mov_b64_e32 v[54:55], s[94:95]
	v_mad_u64_u32 v[54:55], s[30:31], v53, s82, v[54:55]
	v_mad_i32_i24 v55, s75, v201, v55
	v_lshl_add_u64 v[54:55], v[54:55], 0, s[84:85]
	v_lshl_add_u64 v[54:55], v[54:55], 0, v[38:39]
	global_load_dwordx4 v[26:29], v[54:55], off offset:2048
	global_load_dwordx4 v[40:43], v[54:55], off offset:2304
	v_add_u32_e32 v52, s29, v87
	v_cmp_gt_u32_e64 s[44:45], s6, v52
	v_and_b32_e32 v52, 0xfff, v52
	v_or_b32_e32 v53, s74, v52
	v_mov_b64_e32 v[54:55], s[94:95]
	v_mad_u64_u32 v[54:55], s[30:31], v53, s82, v[54:55]
	v_mad_i32_i24 v55, s75, v201, v55
	v_lshl_add_u64 v[54:55], v[54:55], 0, s[84:85]
	v_lshl_add_u64 v[54:55], v[54:55], 0, v[38:39]
	global_load_dwordx4 v[30:33], v[54:55], off offset:2048
	global_load_dwordx4 v[44:47], v[54:55], off offset:2304
	v_add_u32_e32 v52, s29, v102
	v_cmp_gt_u32_e64 s[46:47], s6, v52
	v_and_b32_e32 v52, 0xfff, v52
	v_or_b32_e32 v53, s74, v52
	v_mov_b64_e32 v[54:55], s[94:95]
	v_mad_u64_u32 v[54:55], s[30:31], v53, s82, v[54:55]
	v_mad_i32_i24 v55, s75, v201, v55
	v_lshl_add_u64 v[54:55], v[54:55], 0, s[84:85]
	v_lshl_add_u64 v[54:55], v[54:55], 0, v[38:39]
	global_load_dwordx4 v[34:37], v[54:55], off offset:2048
	global_load_dwordx4 v[48:51], v[54:55], off offset:2304
	v_add_u32_e32 v52, s29, v106
	v_cmp_gt_u32_e64 s[48:49], s6, v52
	v_and_b32_e32 v52, 0xfff, v52
	v_or_b32_e32 v53, s74, v52
	v_mov_b64_e32 v[54:55], s[94:95]
	v_mad_u64_u32 v[54:55], s[30:31], v53, s82, v[54:55]
	v_mad_i32_i24 v55, s75, v201, v55
	v_lshl_add_u64 v[54:55], v[54:55], 0, s[84:85]
	v_lshl_add_u64 v[54:55], v[54:55], 0, v[38:39]
	global_load_dwordx4 v[6:9], v[54:55], off offset:2048
	global_load_dwordx4 v[2:5], v[54:55], off offset:2304
	v_add_u32_e32 v52, s29, v107
	v_cmp_gt_u32_e64 s[50:51], s6, v52
	v_and_b32_e32 v52, 0xfff, v52
	v_or_b32_e32 v53, s74, v52
	v_mov_b64_e32 v[54:55], s[94:95]
	v_mad_u64_u32 v[54:55], s[30:31], v53, s82, v[54:55]
	v_mad_i32_i24 v55, s75, v201, v55
	v_lshl_add_u64 v[54:55], v[54:55], 0, s[84:85]
	v_lshl_add_u64 v[54:55], v[54:55], 0, v[38:39]
	global_load_dwordx4 v[14:17], v[54:55], off offset:2048
	global_load_dwordx4 v[10:13], v[54:55], off offset:2304
	v_add_u32_e32 v52, s29, v108
	v_cmp_gt_u32_e64 s[76:77], s6, v52
	v_and_b32_e32 v52, 0xfff, v52
	v_or_b32_e32 v53, s74, v52
	v_mov_b64_e32 v[54:55], s[94:95]
	v_mad_u64_u32 v[54:55], s[30:31], v53, s82, v[54:55]
	v_mad_i32_i24 v55, s75, v201, v55
	v_lshl_add_u64 v[54:55], v[54:55], 0, s[84:85]
	v_lshl_add_u64 v[54:55], v[54:55], 0, v[38:39]
	global_load_dwordx4 v[22:25], v[54:55], off offset:2048
	global_load_dwordx4 v[18:21], v[54:55], off offset:2304
	s_waitcnt vmcnt(11)
	v_cndmask_b32_e64 v26, 0, v26, s[42:43]
	v_cndmask_b32_e64 v27, 0, v27, s[42:43]
	v_cndmask_b32_e64 v28, 0, v28, s[42:43]
	v_cndmask_b32_e64 v29, 0, v29, s[42:43]
	ds_write_b128 v118, v[26:29]
	s_waitcnt vmcnt(10)
	v_cndmask_b32_e64 v40, 0, v40, s[42:43]
	v_cndmask_b32_e64 v41, 0, v41, s[42:43]
	v_cndmask_b32_e64 v42, 0, v42, s[42:43]
	v_cndmask_b32_e64 v43, 0, v43, s[42:43]
	ds_write_b16 v103, v40 offset:55296
	ds_write_b16_d16_hi v103, v40 offset:56072
	ds_write_b16 v103, v41 offset:56848
	ds_write_b16_d16_hi v103, v41 offset:57624
	ds_write_b16 v103, v42 offset:58400
	ds_write_b16_d16_hi v103, v42 offset:59176
	ds_write_b16 v103, v43 offset:59952
	ds_write_b16_d16_hi v103, v43 offset:60728
	s_waitcnt vmcnt(9)
; #define LAS __attribute__((address_space(3)))
; __device__ __forceinline__ void attn_unit(LAS unsigned char* lds, const bf16* PROJ, bf16* DA, const float* sinkl, int unit, int tid, int wid, int lane) {
;     ...
; #pragma unroll
;         for (int i = 0; i < 3; ++i) {
;             const int idx = tid + 512 * (3 * hp + i), c = idx >> 3, ch = idx & 7;
;             *(LAS v4u*)(Ks + c * KS_PITCH + ch * 8) = kreg[i];
;             LAS bf16* vp = Vt + (ch * 8) * VT_PITCH + c;
;             vp[0 * VT_PITCH] = (bf16)(vreg[i].x & 0xffffu); vp[1 * VT_PITCH] = (bf16)(vreg[i].x >> 16);
;             vp[2 * VT_PITCH] = (bf16)(vreg[i].y & 0xffffu); vp[3 * VT_PITCH] = (bf16)(vreg[i].y >> 16);
;             vp[4 * VT_PITCH] = (bf16)(vreg[i].z & 0xffffu); vp[5 * VT_PITCH] = (bf16)(vreg[i].z >> 16);
;             vp[6 * VT_PITCH] = (bf16)(vreg[i].w & 0xffffu); vp[7 * VT_PITCH] = (bf16)(vreg[i].w >> 16);
;         }
;     }
;     __syncthreads();
;     const int r32 = lane & 31, hi = lane >> 5;
;     const int hq = hk * 4 + (wid >> 1);
;     const float slope2 = __builtin_amdgcn_exp2f(-(float)(hq + 1)) * LOG2E;
;     const float sink2 = sinkl[hq] * LOG2E;
	v_cndmask_b32_e64 v30, 0, v30, s[44:45]
	v_cndmask_b32_e64 v31, 0, v31, s[44:45]
	v_cndmask_b32_e64 v32, 0, v32, s[44:45]
	v_cndmask_b32_e64 v33, 0, v33, s[44:45]
	ds_write_b128 v119, v[30:33]
	s_waitcnt vmcnt(8)
	v_cndmask_b32_e64 v44, 0, v44, s[44:45]
	v_cndmask_b32_e64 v45, 0, v45, s[44:45]
	v_cndmask_b32_e64 v46, 0, v46, s[44:45]
	v_cndmask_b32_e64 v47, 0, v47, s[44:45]
	ds_write_b16 v104, v44 offset:55296
	ds_write_b16_d16_hi v104, v44 offset:56072
	ds_write_b16 v104, v45 offset:56848
	ds_write_b16_d16_hi v104, v45 offset:57624
	ds_write_b16 v104, v46 offset:58400
	ds_write_b16_d16_hi v104, v46 offset:59176
	ds_write_b16 v104, v47 offset:59952
	ds_write_b16_d16_hi v104, v47 offset:60728
	s_waitcnt vmcnt(7)
	v_cndmask_b32_e64 v34, 0, v34, s[46:47]
	v_cndmask_b32_e64 v35, 0, v35, s[46:47]
	v_cndmask_b32_e64 v36, 0, v36, s[46:47]
	v_cndmask_b32_e64 v37, 0, v37, s[46:47]
	ds_write_b128 v120, v[34:37]
	s_waitcnt vmcnt(6)
	v_cndmask_b32_e64 v48, 0, v48, s[46:47]
	v_cndmask_b32_e64 v49, 0, v49, s[46:47]
	v_cndmask_b32_e64 v50, 0, v50, s[46:47]
	v_cndmask_b32_e64 v51, 0, v51, s[46:47]
	ds_write_b16 v105, v48 offset:55296
	ds_write_b16_d16_hi v105, v48 offset:56072
	ds_write_b16 v105, v49 offset:56848
	ds_write_b16_d16_hi v105, v49 offset:57624
	ds_write_b16 v105, v50 offset:58400
	ds_write_b16_d16_hi v105, v50 offset:59176
	ds_write_b16 v105, v51 offset:59952
	ds_write_b16_d16_hi v105, v51 offset:60728
	s_waitcnt vmcnt(5)
	v_cndmask_b32_e64 v6, 0, v6, s[48:49]
	v_cndmask_b32_e64 v7, 0, v7, s[48:49]
	v_cndmask_b32_e64 v8, 0, v8, s[48:49]
	v_cndmask_b32_e64 v9, 0, v9, s[48:49]
	ds_write_b128 v121, v[6:9]
	s_waitcnt vmcnt(4)
	v_cndmask_b32_e64 v2, 0, v2, s[48:49]
	v_cndmask_b32_e64 v3, 0, v3, s[48:49]
	v_cndmask_b32_e64 v4, 0, v4, s[48:49]
	v_cndmask_b32_e64 v5, 0, v5, s[48:49]
	ds_write_b16 v109, v2 offset:55296
	ds_write_b16_d16_hi v109, v2 offset:56072
	ds_write_b16 v109, v3 offset:56848
	ds_write_b16_d16_hi v109, v3 offset:57624
	ds_write_b16 v109, v4 offset:58400
	ds_write_b16_d16_hi v109, v4 offset:59176
	ds_write_b16 v109, v5 offset:59952
	ds_write_b16_d16_hi v109, v5 offset:60728
	s_waitcnt vmcnt(3)
	v_cndmask_b32_e64 v14, 0, v14, s[50:51]
	v_cndmask_b32_e64 v15, 0, v15, s[50:51]
	v_cndmask_b32_e64 v16, 0, v16, s[50:51]
	v_cndmask_b32_e64 v17, 0, v17, s[50:51]
	ds_write_b128 v122, v[14:17]
	s_waitcnt vmcnt(2)
	v_cndmask_b32_e64 v10, 0, v10, s[50:51]
	v_cndmask_b32_e64 v11, 0, v11, s[50:51]
	v_cndmask_b32_e64 v12, 0, v12, s[50:51]
	v_cndmask_b32_e64 v13, 0, v13, s[50:51]
	ds_write_b16 v110, v10 offset:55296
	ds_write_b16_d16_hi v110, v10 offset:56072
	ds_write_b16 v110, v11 offset:56848
	ds_write_b16_d16_hi v110, v11 offset:57624
	ds_write_b16 v110, v12 offset:58400
	ds_write_b16_d16_hi v110, v12 offset:59176
	ds_write_b16 v110, v13 offset:59952
	ds_write_b16_d16_hi v110, v13 offset:60728
	s_waitcnt vmcnt(1)
	v_cndmask_b32_e64 v22, 0, v22, s[76:77]
	v_cndmask_b32_e64 v23, 0, v23, s[76:77]
	v_cndmask_b32_e64 v24, 0, v24, s[76:77]
	v_cndmask_b32_e64 v25, 0, v25, s[76:77]
	ds_write_b128 v123, v[22:25]
	s_waitcnt vmcnt(0)
	v_cndmask_b32_e64 v18, 0, v18, s[76:77]
	v_cndmask_b32_e64 v19, 0, v19, s[76:77]
	v_cndmask_b32_e64 v20, 0, v20, s[76:77]
	v_cndmask_b32_e64 v21, 0, v21, s[76:77]
	ds_write_b16 v111, v18 offset:55296
	ds_write_b16_d16_hi v111, v18 offset:56072
	ds_write_b16 v111, v19 offset:56848
	ds_write_b16_d16_hi v111, v19 offset:57624
	ds_write_b16 v111, v20 offset:58400
	ds_write_b16_d16_hi v111, v20 offset:59176
	ds_write_b16 v111, v21 offset:59952
	ds_write_b16_d16_hi v111, v21 offset:60728
	s_lshl_b32 s27, s27, 2
	s_add_i32 s27, s27, s62
	s_add_i32 s29, s27, 1
	v_cvt_f32_u32_e32 v2, s29
	s_lshl_b32 s29, s27, 2
	s_movk_i32 s6, 0xfff
	s_waitcnt lgkmcnt(0)
	s_barrier
	v_exp_f32_e64 v2, -v2
	s_and_b32 s28, s23, 31
	s_lshl_b32 s28, s28, 7
	v_mul_f32_e32 v92, 0x3fb8aa3b, v2
	s_lshl_b32 s84, s27, 7
	v_mov_b32_e32 v93, v92
	v_lshl_add_u64 v[94:95], v[88:89], 0, s[84:85]
	v_lshl_add_u64 v[96:97], v[90:91], 0, s[84:85]
	v_subrev_u32_e32 v124, s28, v116
	s_mov_b32 s36, 0
	s_mov_b64 s[38:39], -1
	s_mov_b32 s27, 0
	v_mul_f32_e32 v67, 0x3fb8aa3b, v56
	s_branch .LBB0_308

; #define ATT_QK(dst, cblk) do { _Pragma("unroll") for (int r = 0; r < 16; ++r) dst[r] = 0.f; \
;             _Pragma("unroll") for (int ks = 0; ks < 4; ++ks) { const bf16x8 kf = *(const LAS bf16x8*)(Ks + ((cblk) + r32) * KS_PITCH + ks * 16 + hi * 8); \
;                 dst = __builtin_amdgcn_mfma_f32_32x32x16_bf16(kf, qf[ks], dst, 0, 0, 0); } } while (0)
; __device__ __forceinline__ void attn_unit(LAS unsigned char* lds, const bf16* PROJ, bf16* DA, const float* sinkl, int unit, int tid, int wid, int lane) {
;     ...
;         const int a0 = 64 * (wid & 1) + 32 * sb, a = a0 + r32;
;         const size_t qrow = rowb + (size_t)n * 128 + a;
;         bf16x8 qf[4];
; #pragma unroll
;         for (int ks = 0; ks < 4; ++ks) qf[ks] = *(const bf16x8*)(PROJ + qrow * INW + 512 + hq * 64 + ks * 16 + hi * 8);
;         float mrun = sink2, l = 0.f;
;         f32x16 o0, o1;
; #pragma unroll
;         for (int r = 0; r < 16; ++r) { o0[r] = 0.f; o1[r] = 0.f; }
;         const float fb0 = (float)(r32 + 128 - 4 * hi);
;         f32x16 pn;
;     ...
;         ATT_QK(pn, a0);
.LBB0_308:
	s_or_b32 s28, s27, s80
	v_or_b32_e32 v4, s28, v112
	v_or_b32_e32 v2, s26, v4
	v_or_b32_e32 v98, s74, v2
	v_mad_u64_u32 v[2:3], s[28:29], v98, s82, v[94:95]
	v_mad_i32_i24 v3, s75, v201, v3
	s_cmp_eq_u32 s27, 0
	s_cbranch_scc1 .Lq_skip0
	global_load_dwordx4 v[68:71], v[2:3], off offset:1024
	global_load_dwordx4 v[72:75], v[2:3], off offset:1056
	global_load_dwordx4 v[76:79], v[2:3], off offset:1088
	global_load_dwordx4 v[80:83], v[2:3], off offset:1120
.Lq_skip0:
	v_mad_u32_u24 v26, v4, s3, v86
	ds_read_b128 v[18:21], v26
	ds_read_b128 v[22:25], v26 offset:32
	s_mov_b32 s37, s36
	s_xor_b64 s[76:77], s[38:39], -1
	s_mov_b32 s38, s36
	s_mov_b32 s39, s36
	s_mov_b32 s40, s36
	s_mov_b32 s41, s36
	s_mov_b32 s42, s36
	s_mov_b32 s43, s36
	s_mov_b32 s44, s36
	s_mov_b32 s45, s36
	s_mov_b32 s46, s36
	s_mov_b32 s47, s36
	s_mov_b32 s48, s36
	s_mov_b32 s49, s36
	s_mov_b32 s50, s36
	s_mov_b32 s51, s36
	v_mov_b64_e32 v[2:3], s[36:37]
	v_mov_b64_e32 v[16:17], s[50:51]
	s_lshl_b32 s28, s27, 1
	v_mov_b64_e32 v[4:5], s[38:39]
	v_mov_b64_e32 v[6:7], s[40:41]
	v_mov_b64_e32 v[8:9], s[42:43]
	v_mov_b64_e32 v[10:11], s[44:45]
	v_mov_b64_e32 v[12:13], s[46:47]
	v_mov_b64_e32 v[14:15], s[48:49]
	v_add_u32_e32 v125, s28, v114
	v_add_u32_e32 v126, s28, v115
	v_mov_b32_e32 v99, s75
	v_subrev_u32_e32 v127, s27, v124
	v_mov_b32_e32 v128, v67
	s_waitcnt vmcnt(3) lgkmcnt(1)
	v_mfma_f32_32x32x16_bf16 v[50:65], v[18:21], v[68:71], 0
	ds_read_b128 v[18:21], v26 offset:64
	s_waitcnt vmcnt(2) lgkmcnt(1)
	v_mfma_f32_32x32x16_bf16 v[50:65], v[22:25], v[72:75], v[50:65]
	s_waitcnt vmcnt(1) lgkmcnt(0)
	v_mfma_f32_32x32x16_bf16 v[50:65], v[18:21], v[76:79], v[50:65]
	ds_read_b128 v[18:21], v26 offset:96
	s_waitcnt vmcnt(0) lgkmcnt(0)
	v_mfma_f32_32x32x16_bf16 v[50:65], v[18:21], v[80:83], v[50:65]
	v_add_u32_e32 v18, s27, v117
	v_mad_u64_u32 v[100:101], s[28:29], v18, s3, v[86:87]
	v_mov_b64_e32 v[32:33], v[16:17]
	v_mov_b32_e32 v101, 0
	s_mov_b32 s27, 0
	s_mov_b32 s28, 0
	s_nop 5
	v_mov_b64_e32 v[34:35], v[50:51]
	v_mov_b64_e32 v[30:31], v[14:15]
	v_mov_b64_e32 v[28:29], v[12:13]
	v_mov_b64_e32 v[26:27], v[10:11]
	v_mov_b64_e32 v[24:25], v[8:9]
	v_mov_b64_e32 v[22:23], v[6:7]
	v_mov_b64_e32 v[20:21], v[4:5]
	v_mov_b64_e32 v[18:19], v[2:3]
	v_mov_b64_e32 v[36:37], v[52:53]
	v_mov_b64_e32 v[38:39], v[54:55]
	v_mov_b64_e32 v[40:41], v[56:57]
	v_mov_b64_e32 v[42:43], v[58:59]
	v_mov_b64_e32 v[44:45], v[60:61]
	v_mov_b64_e32 v[46:47], v[62:63]
	v_mov_b64_e32 v[48:49], v[64:65]
	s_cmpk_eq_i32 s27, 0xff00
	s_cbranch_scc1 .LBB0_310
